# diff attention: softmax denominators on the VALU (f32 sums of the exponentials) instead of ones-operand MFMAs, on top of the 8-deep K fragment schedule
# baseline (speedup 1.0000x reference)
.LBB0_139:
	v_mov_b32_e32 v248, v108
	v_mov_b32_e32 v249, v92
	s_nop 1
	v_permlane16_swap_b32_e32 v108, v248
	v_permlane16_swap_b32_e32 v92, v249
	v_add_f32_e32 v108, v108, v248
	v_add_f32_e32 v92, v92, v249
	v_mov_b32_e32 v248, v108
	v_mov_b32_e32 v249, v92
	s_nop 1
	v_permlane32_swap_b32_e32 v108, v248
	v_permlane32_swap_b32_e32 v92, v249
	v_add_f32_e32 v108, v108, v248
	v_add_f32_e32 v92, v92, v249
	s_lshl_b64 s[0:1], s[6:7], 10
	s_add_u32 s0, s18, s0
	s_addc_u32 s1, s19, s1
	s_add_u32 s6, s0, s71
	s_addc_u32 s7, s1, 0
	v_div_scale_f32 v0, s[0:1], v108, v108, 1.0
	v_rcp_f32_e32 v1, v0
	v_lshlrev_b32_e32 v192, 1, v234
	s_add_i32 s70, s70, s76
	s_cmpk_lt_i32 s70, 0x100
	v_fma_f32 v2, -v0, v1, 1.0
	v_fmac_f32_e32 v1, v2, v1
	v_div_scale_f32 v2, vcc, 1.0, v108, 1.0
	v_mul_f32_e32 v3, v2, v1
	v_fma_f32 v4, -v0, v3, v2
	v_fmac_f32_e32 v3, v4, v1
	v_fma_f32 v0, -v0, v3, v2
	v_div_fmas_f32 v0, v0, v1, v3
	v_div_scale_f32 v1, s[0:1], v92, v92, v225
	v_rcp_f32_e32 v2, v1
	v_div_fixup_f32 v0, v0, v108, 1.0
	s_mov_b64 s[0:1], 0x800000
	v_fma_f32 v3, -v1, v2, 1.0
	v_fmac_f32_e32 v2, v3, v2
	v_div_scale_f32 v3, vcc, v225, v92, v225
	v_mul_f32_e32 v4, v3, v2
	v_fma_f32 v5, -v1, v4, v3
	v_fmac_f32_e32 v4, v5, v2
	v_fma_f32 v1, -v1, v4, v3
	v_div_fmas_f32 v1, v1, v2, v4
	v_div_fixup_f32 v2, v1, v92, v225
	v_pk_mul_f32 v[4:5], v[124:125], v[2:3] op_sel_hi:[1,0]
	v_pk_mul_f32 v[6:7], v[126:127], v[2:3] op_sel_hi:[1,0]
	v_pk_fma_f32 v[4:5], v[120:121], v[0:1], v[4:5] op_sel_hi:[1,0,1] neg_lo:[0,0,1] neg_hi:[0,0,1]
	v_pk_fma_f32 v[6:7], v[122:123], v[0:1], v[6:7] op_sel_hi:[1,0,1] neg_lo:[0,0,1] neg_hi:[0,0,1]
	v_mul_f32_e32 v1, v5, v5
	v_mul_f32_e32 v3, v7, v7
	v_fmac_f32_e32 v1, v4, v4
	v_fmac_f32_e32 v3, v6, v6
	v_add_f32_e32 v1, v1, v3
	v_pk_mul_f32 v[8:9], v[116:117], v[2:3] op_sel_hi:[1,0]
	v_pk_mul_f32 v[10:11], v[118:119], v[2:3] op_sel_hi:[1,0]
	v_pk_fma_f32 v[8:9], v[112:113], v[0:1], v[8:9] op_sel_hi:[1,0,1] neg_lo:[0,0,1] neg_hi:[0,0,1]
	v_pk_fma_f32 v[10:11], v[114:115], v[0:1], v[10:11] op_sel_hi:[1,0,1] neg_lo:[0,0,1] neg_hi:[0,0,1]
	v_mul_f32_e32 v3, v9, v9
	v_mul_f32_e32 v12, v11, v11
	v_fmac_f32_e32 v3, v8, v8
	v_fmac_f32_e32 v12, v10, v10
	v_add_f32_e32 v3, v3, v12
	v_add_f32_e32 v1, v1, v3
	v_pk_mul_f32 v[12:13], v[104:105], v[2:3] op_sel_hi:[1,0]
	v_pk_mul_f32 v[14:15], v[106:107], v[2:3] op_sel_hi:[1,0]
	v_pk_fma_f32 v[12:13], v[96:97], v[0:1], v[12:13] op_sel_hi:[1,0,1] neg_lo:[0,0,1] neg_hi:[0,0,1]
	v_pk_fma_f32 v[14:15], v[98:99], v[0:1], v[14:15] op_sel_hi:[1,0,1] neg_lo:[0,0,1] neg_hi:[0,0,1]
	v_mul_f32_e32 v3, v13, v13
	s_waitcnt vmcnt(3)
	v_mul_f32_e32 v16, v15, v15
	v_fmac_f32_e32 v3, v12, v12
	v_fmac_f32_e32 v16, v14, v14
	v_add_f32_e32 v3, v3, v16
	v_add_f32_e32 v1, v3, v1
	v_pk_mul_f32 v[16:17], v[88:89], v[2:3] op_sel_hi:[1,0]
	v_pk_mul_f32 v[18:19], v[90:91], v[2:3] op_sel_hi:[1,0]
	v_pk_fma_f32 v[16:17], v[84:85], v[0:1], v[16:17] op_sel_hi:[1,0,1] neg_lo:[0,0,1] neg_hi:[0,0,1]
	v_pk_fma_f32 v[18:19], v[86:87], v[0:1], v[18:19] op_sel_hi:[1,0,1] neg_lo:[0,0,1] neg_hi:[0,0,1]
	v_mul_f32_e32 v3, v17, v17
	s_waitcnt vmcnt(2)
	v_mul_f32_e32 v20, v19, v19
	v_fmac_f32_e32 v3, v16, v16
	v_fmac_f32_e32 v20, v18, v18
	v_add_f32_e32 v3, v3, v20
	v_add_f32_e32 v1, v3, v1
	v_pk_mul_f32 v[20:21], v[76:77], v[2:3] op_sel_hi:[1,0]
	v_pk_mul_f32 v[22:23], v[78:79], v[2:3] op_sel_hi:[1,0]
	v_pk_fma_f32 v[20:21], v[68:69], v[0:1], v[20:21] op_sel_hi:[1,0,1] neg_lo:[0,0,1] neg_hi:[0,0,1]
	v_pk_fma_f32 v[22:23], v[70:71], v[0:1], v[22:23] op_sel_hi:[1,0,1] neg_lo:[0,0,1] neg_hi:[0,0,1]
	v_mul_f32_e32 v3, v21, v21
	s_waitcnt vmcnt(1)
	v_mul_f32_e32 v24, v23, v23
	v_fmac_f32_e32 v3, v20, v20
	v_fmac_f32_e32 v24, v22, v22
	v_add_f32_e32 v3, v3, v24
	v_add_f32_e32 v1, v3, v1
	v_pk_mul_f32 v[24:25], v[64:65], v[2:3] op_sel_hi:[1,0]
	v_pk_mul_f32 v[26:27], v[66:67], v[2:3] op_sel_hi:[1,0]
	v_pk_fma_f32 v[24:25], v[60:61], v[0:1], v[24:25] op_sel_hi:[1,0,1] neg_lo:[0,0,1] neg_hi:[0,0,1]
	v_pk_fma_f32 v[26:27], v[62:63], v[0:1], v[26:27] op_sel_hi:[1,0,1] neg_lo:[0,0,1] neg_hi:[0,0,1]
	v_mul_f32_e32 v3, v25, v25
	s_waitcnt vmcnt(0)
	v_mul_f32_e32 v28, v27, v27
	v_fmac_f32_e32 v3, v24, v24
	v_fmac_f32_e32 v28, v26, v26
	v_add_f32_e32 v3, v3, v28
	v_add_f32_e32 v1, v3, v1
	v_pk_mul_f32 v[28:29], v[52:53], v[2:3] op_sel_hi:[1,0]
	v_pk_mul_f32 v[30:31], v[54:55], v[2:3] op_sel_hi:[1,0]
	v_pk_fma_f32 v[28:29], v[48:49], v[0:1], v[28:29] op_sel_hi:[1,0,1] neg_lo:[0,0,1] neg_hi:[0,0,1]
	v_pk_fma_f32 v[30:31], v[50:51], v[0:1], v[30:31] op_sel_hi:[1,0,1] neg_lo:[0,0,1] neg_hi:[0,0,1]
	v_mul_f32_e32 v3, v29, v29
	v_mul_f32_e32 v40, v31, v31
	v_fmac_f32_e32 v3, v28, v28
	v_fmac_f32_e32 v40, v30, v30
	v_add_f32_e32 v3, v3, v40
	v_add_f32_e32 v40, v3, v1
	v_pk_mul_f32 v[36:37], v[36:37], v[2:3] op_sel_hi:[1,0]
	v_pk_mul_f32 v[2:3], v[38:39], v[2:3] op_sel_hi:[1,0]
	s_nop 0
	v_pk_fma_f32 v[2:3], v[34:35], v[0:1], v[2:3] op_sel_hi:[1,0,1] neg_lo:[0,0,1] neg_hi:[0,0,1]
	v_pk_fma_f32 v[0:1], v[32:33], v[0:1], v[36:37] op_sel_hi:[1,0,1] neg_lo:[0,0,1] neg_hi:[0,0,1]
	v_mul_f32_e32 v33, v3, v3
	v_mul_f32_e32 v32, v1, v1
	v_fmac_f32_e32 v32, v0, v0
	v_fmac_f32_e32 v33, v2, v2
	v_add_f32_e32 v32, v32, v33
	v_add_f32_e32 v32, v32, v40
	v_mov_b32_e32 v33, v32
	s_nop 1
	v_permlane16_swap_b32_e32 v32, v33
	v_add_f32_e32 v32, v32, v33
	v_mov_b32_e32 v33, v32
	s_nop 1
	v_permlane32_swap_b32_e32 v32, v33
	v_add_f32_e32 v32, v32, v33
	v_fmamk_f32 v32, v32, 0x3c000000, v221
	v_cmp_gt_f32_e32 vcc, s97, v32
	v_mul_f32_e32 v33, 0x4b800000, v32
	v_lshlrev_b64 v[34:35], 10, v[202:203]
	v_cndmask_b32_e32 v32, v32, v33, vcc
	v_rsq_f32_e32 v32, v32
	v_lshl_add_u64 v[34:35], s[6:7], 0, v[34:35]
	v_lshl_add_u64 v[34:35], v[34:35], 0, v[192:193]
	v_lshl_add_u64 v[36:37], v[34:35], 0, s[0:1]
	v_mul_f32_e32 v33, 0x45800000, v32
	v_cndmask_b32_e32 v32, v32, v33, vcc
	v_mul_f32_e32 v32, v226, v32
	v_pk_mul_f32 v[6:7], v[6:7], v[32:33] op_sel_hi:[1,0]
	v_pk_mul_f32 v[4:5], v[4:5], v[32:33] op_sel_hi:[1,0]
	v_pk_mul_f32 v[2:3], v[2:3], v[32:33] op_sel_hi:[1,0]
	v_cvt_pk_bf16_f32 v4, v4, v5
	v_cvt_pk_bf16_f32 v5, v6, v7
	v_add_co_u32_e32 v6, vcc, s97, v34
	v_pk_mul_f32 v[0:1], v[0:1], v[32:33] op_sel_hi:[1,0]
	s_nop 0
	v_addc_co_u32_e32 v7, vcc, 0, v35, vcc
	global_store_dwordx2 v[6:7], v[4:5], off
	v_pk_mul_f32 v[4:5], v[10:11], v[32:33] op_sel_hi:[1,0]
	v_pk_mul_f32 v[6:7], v[8:9], v[32:33] op_sel_hi:[1,0]
	v_cvt_pk_bf16_f32 v0, v0, v1
	v_cvt_pk_bf16_f32 v6, v6, v7
	v_cvt_pk_bf16_f32 v7, v4, v5
	global_store_dwordx2 v[36:37], v[6:7], off offset:32
	v_pk_mul_f32 v[4:5], v[14:15], v[32:33] op_sel_hi:[1,0]
	v_pk_mul_f32 v[6:7], v[12:13], v[32:33] op_sel_hi:[1,0]
	v_cvt_pk_bf16_f32 v1, v2, v3
	v_cvt_pk_bf16_f32 v6, v6, v7
	v_cvt_pk_bf16_f32 v7, v4, v5
	global_store_dwordx2 v[36:37], v[6:7], off offset:64
	v_pk_mul_f32 v[4:5], v[18:19], v[32:33] op_sel_hi:[1,0]
	v_pk_mul_f32 v[6:7], v[16:17], v[32:33] op_sel_hi:[1,0]
	global_store_dwordx2 v[36:37], v[0:1], off offset:224
	v_cvt_pk_bf16_f32 v6, v6, v7
	v_cvt_pk_bf16_f32 v7, v4, v5
	global_store_dwordx2 v[36:37], v[6:7], off offset:96
	v_pk_mul_f32 v[4:5], v[22:23], v[32:33] op_sel_hi:[1,0]
	v_pk_mul_f32 v[6:7], v[20:21], v[32:33] op_sel_hi:[1,0]
	s_nop 0
	v_cvt_pk_bf16_f32 v6, v6, v7
	v_cvt_pk_bf16_f32 v7, v4, v5
	global_store_dwordx2 v[36:37], v[6:7], off offset:128
	v_pk_mul_f32 v[4:5], v[26:27], v[32:33] op_sel_hi:[1,0]
	v_pk_mul_f32 v[6:7], v[24:25], v[32:33] op_sel_hi:[1,0]
	s_nop 0
	v_cvt_pk_bf16_f32 v6, v6, v7
	v_cvt_pk_bf16_f32 v7, v4, v5
	global_store_dwordx2 v[36:37], v[6:7], off offset:160
	v_pk_mul_f32 v[4:5], v[30:31], v[32:33] op_sel_hi:[1,0]
	v_pk_mul_f32 v[6:7], v[28:29], v[32:33] op_sel_hi:[1,0]
	s_nop 0
	v_cvt_pk_bf16_f32 v6, v6, v7
	v_cvt_pk_bf16_f32 v7, v4, v5
	global_store_dwordx2 v[36:37], v[6:7], off offset:192
	s_cbranch_scc0 .LBB0_155

.LBB0_146:
	v_exp_f32_e32 v52, v52
	v_exp_f32_e32 v53, v53
	v_exp_f32_e32 v54, v54
	v_exp_f32_e32 v55, v55
	v_exp_f32_e32 v48, v48
	v_exp_f32_e32 v49, v49
	v_exp_f32_e32 v56, v56
	v_exp_f32_e32 v57, v57
	v_exp_f32_e32 v58, v58
	v_exp_f32_e32 v59, v59
	v_add_f32_e32 v249, v52, v53
	v_add_f32_e32 v249, v249, v54
	v_add_f32_e32 v249, v249, v55
	v_add_f32_e32 v249, v249, v56
	v_add_f32_e32 v249, v249, v57
	v_add_f32_e32 v249, v249, v58
	v_add_f32_e32 v249, v249, v59
	v_exp_f32_e32 v68, v68
	v_exp_f32_e32 v69, v69
	v_exp_f32_e32 v70, v70
	v_exp_f32_e32 v71, v71
	v_exp_f32_e32 v80, v72
	v_exp_f32_e32 v81, v73
	v_exp_f32_e32 v82, v74
	v_exp_f32_e32 v83, v75
	v_cvt_pk_bf16_f32 v72, v52, v53
	v_cvt_pk_bf16_f32 v73, v54, v55
	v_add_f32_e32 v249, v249, v68
	v_add_f32_e32 v249, v249, v69
	v_add_f32_e32 v249, v249, v70
	v_add_f32_e32 v249, v249, v71
	v_add_f32_e32 v249, v249, v80
	v_add_f32_e32 v249, v249, v81
	v_add_f32_e32 v249, v249, v82
	v_add_f32_e32 v249, v249, v83
	v_exp_f32_e32 v50, v50
	v_exp_f32_e32 v51, v51
	v_exp_f32_e32 v52, v60
	v_exp_f32_e32 v53, v61
	v_exp_f32_e32 v54, v62
	v_exp_f32_e32 v55, v63
	v_exp_f32_e32 v60, v64
	v_exp_f32_e32 v61, v65
	v_exp_f32_e32 v62, v66
	v_exp_f32_e32 v63, v67
	v_exp_f32_e32 v64, v76
	v_exp_f32_e32 v65, v77
	v_exp_f32_e32 v66, v78
	v_exp_f32_e32 v67, v79
	v_lshlrev_b32_e32 v234, 2, v93
	v_add_f32_e32 v248, v48, v49
	v_add_f32_e32 v248, v248, v50
	v_add_f32_e32 v248, v248, v51
	v_add_f32_e32 v248, v248, v52
	v_add_f32_e32 v248, v248, v53
	v_add_f32_e32 v248, v248, v54
	v_add_f32_e32 v248, v248, v55
	v_add_f32_e32 v248, v248, v60
	v_add_f32_e32 v248, v248, v61
	v_add_f32_e32 v248, v248, v62
	v_add_f32_e32 v248, v248, v63
	v_add_f32_e32 v248, v248, v64
	v_add_f32_e32 v248, v248, v65
	v_add_f32_e32 v248, v248, v66
	v_add_f32_e32 v248, v248, v67
	v_and_or_b32 v95, v234, 4, v94
	v_cvt_pk_bf16_f32 v100, v48, v49
	s_waitcnt lgkmcnt(0)
	s_barrier
	v_lshlrev_b32_e32 v48, 3, v92
	v_cvt_pk_bf16_f32 v74, v56, v57
	v_cvt_pk_bf16_f32 v75, v58, v59
	v_cvt_pk_bf16_f32 v56, v68, v69
	v_cvt_pk_bf16_f32 v57, v70, v71
	v_cvt_pk_bf16_f32 v58, v80, v81
	v_cvt_pk_bf16_f32 v59, v82, v83
	v_cvt_pk_bf16_f32 v101, v50, v51
	v_cvt_pk_bf16_f32 v102, v52, v53
	v_cvt_pk_bf16_f32 v103, v54, v55
	v_cvt_pk_bf16_f32 v80, v60, v61
	v_cvt_pk_bf16_f32 v81, v62, v63
	v_cvt_pk_bf16_f32 v82, v64, v65
	v_cvt_pk_bf16_f32 v83, v66, v67
	v_lshlrev_b32_e32 v235, 11, v93
	v_lshlrev_b32_e32 v236, 8, v94
	v_and_b32_e32 v237, 24, v48
	v_lshlrev_b32_e32 v238, 5, v95
	v_lshl_add_u64 v[212:213], v[84:85], 1, s[8:9]
	v_lshl_add_u64 v[214:215], v[86:87], 1, s[8:9]
	v_lshl_add_u64 v[216:217], v[88:89], 1, s[8:9]
	v_lshl_add_u64 v[218:219], v[90:91], 1, s[8:9]
	v_mov_b64_e32 v[54:55], v[38:39]
	v_mov_b64_e32 v[50:51], v[34:35]
	v_mov_b64_e32 v[66:67], v[38:39]
	v_mov_b64_e32 v[62:63], v[34:35]
	v_mov_b64_e32 v[78:79], v[38:39]
	v_mov_b64_e32 v[70:71], v[34:35]
	v_mov_b64_e32 v[90:91], v[38:39]
	v_mov_b64_e32 v[86:87], v[34:35]
	v_mov_b64_e32 v[106:107], v[38:39]
	v_mov_b64_e32 v[98:99], v[34:35]
	v_mov_b64_e32 v[118:119], v[38:39]
	v_mov_b64_e32 v[114:115], v[34:35]
	v_mov_b64_e32 v[126:127], v[38:39]
	v_mov_b64_e32 v[122:123], v[34:35]
	v_mov_b64_e32 v[94:95], v[38:39]
	v_mov_b64_e32 v[110:111], v[34:35]
	v_ashrrev_i32_e32 v203, 31, v202
	s_mov_b32 s1, 0
	v_mov_b64_e32 v[52:53], v[36:37]
	v_mov_b64_e32 v[48:49], v[32:33]
	v_mov_b64_e32 v[64:65], v[36:37]
	v_mov_b64_e32 v[60:61], v[32:33]
	v_mov_b64_e32 v[76:77], v[36:37]
	v_mov_b64_e32 v[68:69], v[32:33]
	v_mov_b64_e32 v[88:89], v[36:37]
	v_mov_b64_e32 v[84:85], v[32:33]
	v_mov_b64_e32 v[104:105], v[36:37]
	v_mov_b64_e32 v[96:97], v[32:33]
	v_mov_b64_e32 v[116:117], v[36:37]
	v_mov_b64_e32 v[112:113], v[32:33]
	v_mov_b64_e32 v[124:125], v[36:37]
	v_mov_b64_e32 v[120:121], v[32:33]
	v_mov_b32_e32 v92, v36
	v_mov_b32_e32 v93, v248
	v_mov_b32_e32 v108, v32
	v_mov_b32_e32 v109, v249

.LBB0_153:
	v_add_f32_e32 v108, v108, v109
	v_add_f32_e32 v92, v92, v93
	s_waitcnt lgkmcnt(14)
	v_mfma_f32_16x16x32_bf16 v[120:123], v[156:159], v[72:75], v[120:123]
	v_exp_f32_e32 v188, v188
	v_exp_f32_e32 v189, v189
	v_mfma_f32_16x16x32_bf16 v[124:127], v[156:159], v[100:103], v[124:127]
	v_add_f32_e32 v109, v188, v189
	ds_read_b64_tr_b16 v[156:157], v246 offset:28672
	ds_read_b64_tr_b16 v[158:159], v246 offset:29696
	s_waitcnt lgkmcnt(14)
	v_mfma_f32_16x16x32_bf16 v[112:115], v[152:155], v[72:75], v[112:115]
	v_exp_f32_e32 v190, v190
	v_exp_f32_e32 v191, v191
	v_mfma_f32_16x16x32_bf16 v[116:119], v[152:155], v[100:103], v[116:119]
	v_add_f32_e32 v109, v109, v190
	v_add_f32_e32 v109, v109, v191
	ds_read_b64_tr_b16 v[152:153], v245 offset:28672
	ds_read_b64_tr_b16 v[154:155], v245 offset:29696
	s_waitcnt lgkmcnt(14)
	v_mfma_f32_16x16x32_bf16 v[96:99], v[148:151], v[72:75], v[96:99]
	v_exp_f32_e32 v184, v184
	v_exp_f32_e32 v185, v185
	v_mfma_f32_16x16x32_bf16 v[104:107], v[148:151], v[100:103], v[104:107]
	v_add_f32_e32 v109, v109, v184
	v_add_f32_e32 v109, v109, v185
	ds_read_b64_tr_b16 v[148:149], v244 offset:28672
	ds_read_b64_tr_b16 v[150:151], v244 offset:29696
	s_waitcnt lgkmcnt(14)
	v_mfma_f32_16x16x32_bf16 v[84:87], v[144:147], v[72:75], v[84:87]
	v_exp_f32_e32 v186, v186
	v_exp_f32_e32 v187, v187
	v_mfma_f32_16x16x32_bf16 v[88:91], v[144:147], v[100:103], v[88:91]
	v_add_f32_e32 v109, v109, v186
	v_add_f32_e32 v109, v109, v187
	ds_read_b64_tr_b16 v[144:145], v243 offset:28672
	ds_read_b64_tr_b16 v[146:147], v243 offset:29696
	s_waitcnt lgkmcnt(14)
	v_mfma_f32_16x16x32_bf16 v[68:71], v[140:143], v[72:75], v[68:71]
	v_exp_f32_e32 v194, v180
	v_exp_f32_e32 v195, v181
	v_mfma_f32_16x16x32_bf16 v[76:79], v[140:143], v[100:103], v[76:79]
	v_add_f32_e32 v109, v109, v194
	v_add_f32_e32 v109, v109, v195
	ds_read_b64_tr_b16 v[140:141], v242 offset:28672
	ds_read_b64_tr_b16 v[142:143], v242 offset:29696
	s_waitcnt lgkmcnt(14)
	v_mfma_f32_16x16x32_bf16 v[60:63], v[136:139], v[72:75], v[60:63]
	v_exp_f32_e32 v196, v182
	v_exp_f32_e32 v197, v183
	v_mfma_f32_16x16x32_bf16 v[64:67], v[136:139], v[100:103], v[64:67]
	v_add_f32_e32 v109, v109, v196
	v_add_f32_e32 v109, v109, v197
	ds_read_b64_tr_b16 v[136:137], v241 offset:28672
	ds_read_b64_tr_b16 v[138:139], v241 offset:29696
	s_waitcnt lgkmcnt(14)
	v_mfma_f32_16x16x32_bf16 v[48:51], v[132:135], v[72:75], v[48:51]
	v_exp_f32_e32 v172, v172
	v_exp_f32_e32 v173, v173
	v_mfma_f32_16x16x32_bf16 v[52:55], v[132:135], v[100:103], v[52:55]
	v_add_f32_e32 v109, v109, v172
	v_add_f32_e32 v109, v109, v173
	ds_read_b64_tr_b16 v[132:133], v240 offset:28672
	ds_read_b64_tr_b16 v[134:135], v240 offset:29696
	s_waitcnt lgkmcnt(14)
	v_mfma_f32_16x16x32_bf16 v[32:35], v[128:131], v[72:75], v[32:35]
	ds_read_b64_tr_b16 v[180:181], v239 offset:28672
	ds_read_b64_tr_b16 v[182:183], v239 offset:29696
	v_exp_f32_e32 v174, v174
	v_exp_f32_e32 v175, v175
	v_mfma_f32_16x16x32_bf16 v[36:39], v[128:131], v[100:103], v[36:39]
	v_add_f32_e32 v109, v109, v174
	v_add_f32_e32 v109, v109, v175
	s_waitcnt lgkmcnt(14)
	v_mfma_f32_16x16x32_bf16 v[120:123], v[156:159], v[56:59], v[120:123]
	v_exp_f32_e32 v100, v160
	v_exp_f32_e32 v101, v161
	v_cvt_pk_bf16_f32 v72, v188, v189
	v_mfma_f32_16x16x32_bf16 v[124:127], v[156:159], v[80:83], v[124:127]
	v_add_f32_e32 v93, v100, v101
	v_cvt_pk_bf16_f32 v73, v190, v191
	v_cvt_pk_bf16_f32 v74, v184, v185
	v_cvt_pk_bf16_f32 v75, v186, v187
	s_waitcnt lgkmcnt(12)
	v_mfma_f32_16x16x32_bf16 v[112:115], v[152:155], v[56:59], v[112:115]
	v_exp_f32_e32 v102, v162
	v_exp_f32_e32 v103, v163
	v_mfma_f32_16x16x32_bf16 v[116:119], v[152:155], v[80:83], v[116:119]
	v_add_f32_e32 v93, v93, v102
	v_add_f32_e32 v93, v93, v103
	s_waitcnt lgkmcnt(10)
	v_mfma_f32_16x16x32_bf16 v[96:99], v[148:151], v[56:59], v[96:99]
	v_exp_f32_e32 v152, v168
	v_exp_f32_e32 v153, v169
	v_mfma_f32_16x16x32_bf16 v[104:107], v[148:151], v[80:83], v[104:107]
	v_add_f32_e32 v93, v93, v152
	v_add_f32_e32 v93, v93, v153
	s_waitcnt lgkmcnt(8)
	v_mfma_f32_16x16x32_bf16 v[84:87], v[144:147], v[56:59], v[84:87]
	v_exp_f32_e32 v148, v170
	v_exp_f32_e32 v149, v171
	v_mfma_f32_16x16x32_bf16 v[88:91], v[144:147], v[80:83], v[88:91]
	v_add_f32_e32 v93, v93, v148
	v_add_f32_e32 v93, v93, v149
	s_waitcnt lgkmcnt(6)
	v_mfma_f32_16x16x32_bf16 v[68:71], v[140:143], v[56:59], v[68:71]
	v_cvt_pk_bf16_f32 v100, v100, v101
	v_cvt_pk_bf16_f32 v101, v102, v103
	v_cvt_pk_bf16_f32 v102, v152, v153
	v_mfma_f32_16x16x32_bf16 v[76:79], v[140:143], v[80:83], v[76:79]
	v_cvt_pk_bf16_f32 v103, v148, v149
	v_exp_f32_e32 v140, v164
	v_exp_f32_e32 v141, v165
	s_waitcnt lgkmcnt(4)
	v_mfma_f32_16x16x32_bf16 v[60:63], v[136:139], v[56:59], v[60:63]
	v_add_f32_e32 v93, v93, v140
	v_add_f32_e32 v93, v93, v141
	v_exp_f32_e32 v142, v166
	v_exp_f32_e32 v143, v167
	v_mfma_f32_16x16x32_bf16 v[64:67], v[136:139], v[80:83], v[64:67]
	v_add_f32_e32 v93, v93, v142
	v_add_f32_e32 v93, v93, v143
	s_waitcnt lgkmcnt(2)
	v_mfma_f32_16x16x32_bf16 v[48:51], v[132:135], v[56:59], v[48:51]
	v_exp_f32_e32 v136, v176
	v_exp_f32_e32 v137, v177
	v_mfma_f32_16x16x32_bf16 v[52:55], v[132:135], v[80:83], v[52:55]
	v_add_f32_e32 v93, v93, v136
	v_add_f32_e32 v93, v93, v137
	s_waitcnt lgkmcnt(0)
	v_mfma_f32_16x16x32_bf16 v[32:35], v[180:183], v[56:59], v[32:35]
	v_exp_f32_e32 v132, v178
	v_exp_f32_e32 v133, v179
	v_mfma_f32_16x16x32_bf16 v[36:39], v[180:183], v[80:83], v[36:39]
	v_add_f32_e32 v93, v93, v132
	v_add_f32_e32 v93, v93, v133
	s_waitcnt lgkmcnt(0)
	s_barrier
	v_cvt_pk_bf16_f32 v56, v194, v195
	v_cvt_pk_bf16_f32 v57, v196, v197
	v_cvt_pk_bf16_f32 v58, v172, v173
	v_cvt_pk_bf16_f32 v59, v174, v175
	v_cvt_pk_bf16_f32 v80, v140, v141
	v_cvt_pk_bf16_f32 v81, v142, v143
	v_cvt_pk_bf16_f32 v82, v136, v137
	v_cvt_pk_bf16_f32 v83, v132, v133
	s_cmp_lg_u32 s82, s8
	s_cbranch_scc0 .LBB0_139
	s_mov_b32 s1, s8
	s_branch .LBB0_147
